# LayerNorm passes: first row load waited at its use (counted), all 8 loads in flight together
# baseline (speedup 1.0000x reference)
;     ...
;     for (int row = vb * 8 + w; row < TT; row += 2 * stride) {
;         const int row2 = row + stride; const bool has2 = row2 < TT;
;         const f32x4* xr = (const f32x4*)(X32 + (size_t)row * DM); const f32x4* xr2 = (const f32x4*)(X32 + (size_t)(has2 ? row2 : row) * DM);
;         f32x4 v[4], u[4]; float s = 0.f, t = 0.f;
; #pragma unroll
;         for (int j = 0; j < 4; ++j) { v[j] = xr[l + 64 * j]; u[j] = xr2[l + 64 * j]; }
; #pragma unroll
;         for (int j = 0; j < 4; ++j) { s += (v[j].x + v[j].y) + (v[j].z + v[j].w); t += (u[j].x + u[j].y) + (u[j].z + u[j].w); }
;         const float mean = wave_sum(s) * (1.f / DM), mean2 = wave_sum(t) * (1.f / DM); float s2 = 0.f, t2 = 0.f;
; #pragma unroll
;         for (int j = 0; j < 4; ++j) { v[j] = v[j] - mean; u[j] = u[j] - mean2; s2 += (v[j].x * v[j].x + v[j].y * v[j].y) + (v[j].z * v[j].z + v[j].w * v[j].w); t2 += (u[j].x * u[j].x + u[j].y * u[j].y) + (u[j].z * u[j].z + u[j].w * u[j].w); }
;         const float rstd = __builtin_amdgcn_rsqf(wave_sum(s2) * (1.f / DM) + EPS), rstd2 = __builtin_amdgcn_rsqf(wave_sum(t2) * (1.f / DM) + EPS);
.LBB0_1112:
	v_ashrrev_i32_e32 v71, 31, v70
	v_lshlrev_b64 v[34:35], 12, v[70:71]
	v_lshl_add_u64 v[44:45], v[64:65], 0, v[34:35]
	v_add_u32_e32 v68, s31, v70
	s_mov_b32 s0, 0x8000
	global_load_dwordx4 v[60:63], v[44:45], off
	v_cmp_gt_i32_e64 s[0:1], s0, v68
	v_cndmask_b32_e64 v32, v70, v68, s[0:1]
	v_ashrrev_i32_e32 v33, 31, v32
	v_lshlrev_b64 v[32:33], 12, v[32:33]
	v_lshl_add_u64 v[46:47], v[64:65], 0, v[32:33]
	global_load_dwordx4 v[40:43], v[46:47], off
	global_load_dwordx4 v[56:59], v[44:45], off offset:1024
	global_load_dwordx4 v[36:39], v[46:47], off offset:1024
	global_load_dwordx4 v[52:55], v[44:45], off offset:2048
	global_load_dwordx4 v[32:35], v[46:47], off offset:2048
	global_load_dwordx4 v[48:51], v[44:45], off offset:3072
	s_nop 0
	global_load_dwordx4 v[44:47], v[46:47], off offset:3072
	s_waitcnt lgkmcnt(0)
	s_waitcnt vmcnt(7)
	v_mov_b32_e32 v80, v61
	v_mov_b32_e32 v81, v62
	v_mov_b32_e32 v82, v60
	v_mov_b32_e32 v83, v63
	v_pk_add_f32 v[80:81], v[80:81], v[82:83]
	s_waitcnt vmcnt(6)
	v_mov_b32_e32 v82, v41
	v_mov_b32_e32 v83, v42
	v_mov_b32_e32 v84, v40
	v_mov_b32_e32 v85, v43
	v_pk_add_f32 v[82:83], v[82:83], v[84:85]
	s_waitcnt vmcnt(5)
	v_mov_b32_e32 v84, v57
	v_mov_b32_e32 v85, v58
	v_mov_b32_e32 v86, v56
	v_mov_b32_e32 v87, v59
	v_pk_add_f32 v[84:85], v[84:85], v[86:87]
	v_add_f32_e32 v69, v80, v81
	v_pk_add_f32 v[84:85], v[84:85], v[84:85] op_sel:[0,1] op_sel_hi:[1,0]
	s_waitcnt vmcnt(4)
	v_mov_b32_e32 v86, v37
	v_mov_b32_e32 v87, v38
	v_mov_b32_e32 v88, v36
	v_mov_b32_e32 v89, v39
	v_add_f32_e32 v80, 0, v69
	v_pk_add_f32 v[86:87], v[86:87], v[88:89]
	s_waitcnt vmcnt(3)
	v_add_f32_e32 v88, v52, v53
	v_add_f32_e32 v90, v54, v55
	s_waitcnt vmcnt(1)
	v_mov_b32_e32 v81, v48
	v_mov_b32_e32 v85, v49
	v_mov_b32_e32 v89, v50
	v_mov_b32_e32 v91, v51
	v_pk_add_f32 v[80:81], v[80:81], v[84:85]
	v_pk_add_f32 v[84:85], v[88:89], v[90:91]
	v_add_f32_e32 v69, v82, v83
	v_pk_add_f32 v[80:81], v[80:81], v[84:85]
	v_add_f32_e32 v82, 0, v69
	v_add_f32_e32 v69, v80, v81
	ds_bpermute_b32 v79, v73, v69
	v_pk_add_f32 v[86:87], v[86:87], v[86:87] op_sel:[0,1] op_sel_hi:[1,0]
	v_add_f32_e32 v92, v32, v33
	v_add_f32_e32 v94, v34, v35
	s_waitcnt vmcnt(0)
	v_mov_b32_e32 v83, v44
	s_waitcnt lgkmcnt(0)
	v_add_f32_e32 v69, v69, v79
	ds_bpermute_b32 v79, v74, v69
	v_mov_b32_e32 v87, v45
	v_mov_b32_e32 v93, v46
	v_mov_b32_e32 v95, v47
	v_pk_add_f32 v[80:81], v[82:83], v[86:87]
	s_waitcnt lgkmcnt(0)
	v_add_f32_e32 v69, v69, v79
	ds_bpermute_b32 v79, v75, v69
	v_pk_add_f32 v[82:83], v[92:93], v[94:95]
	s_waitcnt lgkmcnt(0)
	v_add_f32_e32 v69, v69, v79
	ds_bpermute_b32 v79, v76, v69
	v_pk_add_f32 v[80:81], v[80:81], v[82:83]
	s_waitcnt lgkmcnt(0)
	v_add_f32_e32 v69, v69, v79
	ds_bpermute_b32 v79, v77, v69
	v_add_f32_e32 v72, v80, v81
	s_waitcnt lgkmcnt(0)
	v_add_f32_e32 v69, v69, v79
	ds_bpermute_b32 v79, v78, v69
	s_waitcnt lgkmcnt(0)
	v_add_f32_e32 v69, v69, v79
	ds_bpermute_b32 v79, v73, v72
	v_fmamk_f32 v62, v69, 0xba800000, v62
	v_fmamk_f32 v61, v69, 0xba800000, v61
	v_fmamk_f32 v63, v69, 0xba800000, v63
	v_fmac_f32_e32 v60, 0xba800000, v69
	s_waitcnt lgkmcnt(0)
	v_add_f32_e32 v72, v72, v79
	ds_bpermute_b32 v79, v74, v72
	v_mul_f32_e32 v80, v62, v62
	v_fmac_f32_e32 v80, v63, v63
	v_fmamk_f32 v58, v69, 0xba800000, v58
	v_fmamk_f32 v57, v69, 0xba800000, v57
	s_waitcnt lgkmcnt(0)
	v_add_f32_e32 v72, v72, v79
	ds_bpermute_b32 v79, v75, v72
	v_fmamk_f32 v59, v69, 0xba800000, v59
	v_fmac_f32_e32 v56, 0xba800000, v69
	v_mul_f32_e32 v82, v58, v58
	v_fmac_f32_e32 v82, v59, v59
	s_waitcnt lgkmcnt(0)
	v_add_f32_e32 v72, v72, v79
	ds_bpermute_b32 v79, v76, v72
	v_fmamk_f32 v54, v69, 0xba800000, v54
	v_fmamk_f32 v53, v69, 0xba800000, v53
	v_fmamk_f32 v55, v69, 0xba800000, v55
	v_fmac_f32_e32 v52, 0xba800000, v69
	s_waitcnt lgkmcnt(0)
	v_add_f32_e32 v72, v72, v79
	ds_bpermute_b32 v79, v77, v72
	v_fmamk_f32 v50, v69, 0xba800000, v50
	v_fmamk_f32 v49, v69, 0xba800000, v49
	v_fmamk_f32 v51, v69, 0xba800000, v51
	v_fmac_f32_e32 v48, 0xba800000, v69
	s_waitcnt lgkmcnt(0)
	v_add_f32_e32 v72, v72, v79
	ds_bpermute_b32 v79, v78, v72
	s_waitcnt lgkmcnt(0)
	v_add_f32_e32 v79, v72, v79
	v_mul_f32_e32 v72, v61, v61
	v_fmamk_f32 v43, v79, 0xba800000, v43
	v_fmamk_f32 v41, v79, 0xba800000, v41
	v_fmac_f32_e32 v72, v60, v60
	v_fmamk_f32 v42, v79, 0xba800000, v42
	v_fmac_f32_e32 v40, 0xba800000, v79
	v_add_f32_e32 v72, v72, v80
	v_mul_f32_e32 v80, v41, v41
	v_mul_f32_e32 v81, v43, v43
	v_fmac_f32_e32 v80, v40, v40
	v_fmac_f32_e32 v81, v42, v42
	v_add_f32_e32 v80, v80, v81
	v_mul_f32_e32 v81, v57, v57
	v_fmac_f32_e32 v81, v56, v56
	v_fmamk_f32 v39, v79, 0xba800000, v39
	v_fmamk_f32 v37, v79, 0xba800000, v37
	v_add_f32_e32 v81, v81, v82
	v_fmamk_f32 v38, v79, 0xba800000, v38
	v_fmac_f32_e32 v36, 0xba800000, v79
	v_add_f32_e32 v72, v72, v81
	v_mul_f32_e32 v81, v37, v37
	v_mul_f32_e32 v82, v39, v39
	v_fmac_f32_e32 v81, v36, v36
	v_fmac_f32_e32 v82, v38, v38
	v_add_f32_e32 v81, v81, v82
	v_add_f32_e32 v80, v80, v81
	v_mul_f32_e32 v81, v53, v53
	v_mul_f32_e32 v82, v54, v54
	v_fmac_f32_e32 v81, v52, v52
	v_fmac_f32_e32 v82, v55, v55
	v_fmamk_f32 v35, v79, 0xba800000, v35
	v_fmamk_f32 v33, v79, 0xba800000, v33
	v_add_f32_e32 v81, v81, v82
	v_fmamk_f32 v34, v79, 0xba800000, v34
	v_fmac_f32_e32 v32, 0xba800000, v79
	v_add_f32_e32 v72, v81, v72
	v_mul_f32_e32 v81, v33, v33
	v_mul_f32_e32 v82, v35, v35
	v_fmac_f32_e32 v81, v32, v32
	v_fmac_f32_e32 v82, v34, v34
	v_add_f32_e32 v81, v81, v82
	v_add_f32_e32 v80, v81, v80
	v_mul_f32_e32 v81, v49, v49
	v_mul_f32_e32 v82, v50, v50
	v_fmac_f32_e32 v81, v48, v48
	v_fmac_f32_e32 v82, v51, v51
	v_fmamk_f32 v47, v79, 0xba800000, v47
	v_fmamk_f32 v45, v79, 0xba800000, v45
	v_add_f32_e32 v81, v81, v82
	v_fmamk_f32 v46, v79, 0xba800000, v46
	v_fmac_f32_e32 v44, 0xba800000, v79
	v_add_f32_e32 v72, v81, v72
	v_mul_f32_e32 v81, v45, v45
	v_mul_f32_e32 v82, v47, v47
	v_fmac_f32_e32 v81, v44, v44
	v_fmac_f32_e32 v82, v46, v46
	v_add_f32_e32 v81, v81, v82
	v_add_f32_e32 v80, v81, v80
	ds_bpermute_b32 v81, v73, v72
	s_waitcnt lgkmcnt(0)
	v_add_f32_e32 v72, v72, v81
	ds_bpermute_b32 v81, v74, v72
	s_waitcnt lgkmcnt(0)
	v_add_f32_e32 v72, v72, v81
	ds_bpermute_b32 v81, v75, v72
	s_waitcnt lgkmcnt(0)
	v_add_f32_e32 v72, v72, v81
	ds_bpermute_b32 v81, v76, v72
	s_waitcnt lgkmcnt(0)
	v_add_f32_e32 v72, v72, v81
	ds_bpermute_b32 v81, v77, v72
	s_waitcnt lgkmcnt(0)
	v_add_f32_e32 v72, v72, v81
	ds_bpermute_b32 v81, v78, v72
	s_waitcnt lgkmcnt(0)
	v_add_f32_e32 v72, v72, v81
	ds_bpermute_b32 v81, v73, v80
	v_fmamk_f32 v72, v72, 0x3a800000, v252
	v_rsq_f32_e32 v72, v72
	s_waitcnt lgkmcnt(0)
	v_add_f32_e32 v80, v80, v81
	ds_bpermute_b32 v81, v74, v80
	s_waitcnt lgkmcnt(0)
	v_add_f32_e32 v80, v80, v81
	ds_bpermute_b32 v81, v75, v80
	s_waitcnt lgkmcnt(0)
	v_add_f32_e32 v80, v80, v81
	ds_bpermute_b32 v81, v76, v80
	s_waitcnt lgkmcnt(0)
	v_add_f32_e32 v80, v80, v81
	ds_bpermute_b32 v81, v77, v80
	s_waitcnt lgkmcnt(0)
	v_add_f32_e32 v80, v80, v81
	ds_bpermute_b32 v81, v78, v80
	s_and_saveexec_b64 s[18:19], vcc
	s_cbranch_execz .LBB0_1114
;     ...
;         if (!dry) {
;             u32x2* xb = (u32x2*)(Xb + (size_t)row * DM);
;             if (l == 0) STATS[row] = (f32x2){mean, rstd};
	v_readlane_b32 s20, v254, 46
	v_readlane_b32 s21, v254, 47
	v_mul_f32_e32 v82, 0x3a800000, v69
	v_mov_b32_e32 v83, v72
	v_lshl_add_u64 v[84:85], v[70:71], 3, s[20:21]
	global_store_dwordx2 v[84:85], v[82:83], off

;     ...
;     for (int row = vb * 8 + w; row < TT; row += 2 * stride) {
;         const int row2 = row + stride; const bool has2 = row2 < TT;
;         const f32x4* xr = (const f32x4*)(X32 + (size_t)row * DM); const f32x4* xr2 = (const f32x4*)(X32 + (size_t)(has2 ? row2 : row) * DM);
;         f32x4 v[4], u[4]; float s = 0.f, t = 0.f;
; #pragma unroll
;         for (int j = 0; j < 4; ++j) { v[j] = xr[l + 64 * j]; u[j] = xr2[l + 64 * j]; }
; #pragma unroll
;         for (int j = 0; j < 4; ++j) { s += (v[j].x + v[j].y) + (v[j].z + v[j].w); t += (u[j].x + u[j].y) + (u[j].z + u[j].w); }
;         const float mean = wave_sum(s) * (1.f / DM), mean2 = wave_sum(t) * (1.f / DM); float s2 = 0.f, t2 = 0.f;
; #pragma unroll
;         for (int j = 0; j < 4; ++j) { v[j] = v[j] - mean; u[j] = u[j] - mean2; s2 += (v[j].x * v[j].x + v[j].y * v[j].y) + (v[j].z * v[j].z + v[j].w * v[j].w); t2 += (u[j].x * u[j].x + u[j].y * u[j].y) + (u[j].z * u[j].z + u[j].w * u[j].w); }
;         const float rstd = __builtin_amdgcn_rsqf(wave_sum(s2) * (1.f / DM) + EPS), rstd2 = __builtin_amdgcn_rsqf(wave_sum(t2) * (1.f / DM) + EPS);
.LBB0_1827:
	v_ashrrev_i32_e32 v71, 31, v70
	v_lshlrev_b64 v[34:35], 12, v[70:71]
	v_lshl_add_u64 v[44:45], v[64:65], 0, v[34:35]
	v_add_u32_e32 v68, s31, v70
	s_mov_b32 s0, 0x8000
	global_load_dwordx4 v[60:63], v[44:45], off
	v_cmp_gt_i32_e64 s[0:1], s0, v68
	v_cndmask_b32_e64 v32, v70, v68, s[0:1]
	v_ashrrev_i32_e32 v33, 31, v32
	v_lshlrev_b64 v[32:33], 12, v[32:33]
	v_lshl_add_u64 v[46:47], v[64:65], 0, v[32:33]
	global_load_dwordx4 v[40:43], v[46:47], off
	global_load_dwordx4 v[56:59], v[44:45], off offset:1024
	global_load_dwordx4 v[36:39], v[46:47], off offset:1024
	global_load_dwordx4 v[52:55], v[44:45], off offset:2048
	global_load_dwordx4 v[32:35], v[46:47], off offset:2048
	global_load_dwordx4 v[48:51], v[44:45], off offset:3072
	s_nop 0
	global_load_dwordx4 v[44:47], v[46:47], off offset:3072
	s_waitcnt lgkmcnt(0)
	s_waitcnt vmcnt(7)
	v_mov_b32_e32 v80, v61
	v_mov_b32_e32 v81, v62
	v_mov_b32_e32 v82, v60
	v_mov_b32_e32 v83, v63
	v_pk_add_f32 v[80:81], v[80:81], v[82:83]
	s_waitcnt vmcnt(6)
	v_mov_b32_e32 v82, v41
	v_mov_b32_e32 v83, v42
	v_mov_b32_e32 v84, v40
	v_mov_b32_e32 v85, v43
	v_pk_add_f32 v[82:83], v[82:83], v[84:85]
	s_waitcnt vmcnt(5)
	v_mov_b32_e32 v84, v57
	v_mov_b32_e32 v85, v58
	v_mov_b32_e32 v86, v56
	v_mov_b32_e32 v87, v59
	v_pk_add_f32 v[84:85], v[84:85], v[86:87]
	v_add_f32_e32 v69, v80, v81
	v_pk_add_f32 v[84:85], v[84:85], v[84:85] op_sel:[0,1] op_sel_hi:[1,0]
	s_waitcnt vmcnt(4)
	v_mov_b32_e32 v86, v37
	v_mov_b32_e32 v87, v38
	v_mov_b32_e32 v88, v36
	v_mov_b32_e32 v89, v39
	v_add_f32_e32 v80, 0, v69
	v_pk_add_f32 v[86:87], v[86:87], v[88:89]
	s_waitcnt vmcnt(3)
	v_add_f32_e32 v88, v52, v53
	v_add_f32_e32 v90, v54, v55
	s_waitcnt vmcnt(1)
	v_mov_b32_e32 v81, v48
	v_mov_b32_e32 v85, v49
	v_mov_b32_e32 v89, v50
	v_mov_b32_e32 v91, v51
	v_pk_add_f32 v[80:81], v[80:81], v[84:85]
	v_pk_add_f32 v[84:85], v[88:89], v[90:91]
	v_add_f32_e32 v69, v82, v83
	v_pk_add_f32 v[80:81], v[80:81], v[84:85]
	v_add_f32_e32 v82, 0, v69
	v_add_f32_e32 v69, v80, v81
	ds_bpermute_b32 v79, v73, v69
	v_pk_add_f32 v[86:87], v[86:87], v[86:87] op_sel:[0,1] op_sel_hi:[1,0]
	v_add_f32_e32 v92, v32, v33
	v_add_f32_e32 v94, v34, v35
	s_waitcnt vmcnt(0)
	v_mov_b32_e32 v83, v44
	s_waitcnt lgkmcnt(0)
	v_add_f32_e32 v69, v69, v79
	ds_bpermute_b32 v79, v74, v69
	v_mov_b32_e32 v87, v45
	v_mov_b32_e32 v93, v46
	v_mov_b32_e32 v95, v47
	v_pk_add_f32 v[80:81], v[82:83], v[86:87]
	s_waitcnt lgkmcnt(0)
	v_add_f32_e32 v69, v69, v79
	ds_bpermute_b32 v79, v75, v69
	v_pk_add_f32 v[82:83], v[92:93], v[94:95]
	s_waitcnt lgkmcnt(0)
	v_add_f32_e32 v69, v69, v79
	ds_bpermute_b32 v79, v76, v69
	v_pk_add_f32 v[80:81], v[80:81], v[82:83]
	s_waitcnt lgkmcnt(0)
	v_add_f32_e32 v69, v69, v79
	ds_bpermute_b32 v79, v77, v69
	v_add_f32_e32 v72, v80, v81
	s_waitcnt lgkmcnt(0)
	v_add_f32_e32 v69, v69, v79
	ds_bpermute_b32 v79, v78, v69
	s_waitcnt lgkmcnt(0)
	v_add_f32_e32 v69, v69, v79
	ds_bpermute_b32 v79, v73, v72
	v_fmamk_f32 v62, v69, 0xba800000, v62
	v_fmamk_f32 v61, v69, 0xba800000, v61
	v_fmamk_f32 v63, v69, 0xba800000, v63
	v_fmac_f32_e32 v60, 0xba800000, v69
	s_waitcnt lgkmcnt(0)
	v_add_f32_e32 v72, v72, v79
	ds_bpermute_b32 v79, v74, v72
	v_mul_f32_e32 v80, v62, v62
	v_fmac_f32_e32 v80, v63, v63
	v_fmamk_f32 v58, v69, 0xba800000, v58
	v_fmamk_f32 v57, v69, 0xba800000, v57
	s_waitcnt lgkmcnt(0)
	v_add_f32_e32 v72, v72, v79
	ds_bpermute_b32 v79, v75, v72
	v_fmamk_f32 v59, v69, 0xba800000, v59
	v_fmac_f32_e32 v56, 0xba800000, v69
	v_mul_f32_e32 v82, v58, v58
	v_fmac_f32_e32 v82, v59, v59
	s_waitcnt lgkmcnt(0)
	v_add_f32_e32 v72, v72, v79
	ds_bpermute_b32 v79, v76, v72
	v_fmamk_f32 v54, v69, 0xba800000, v54
	v_fmamk_f32 v53, v69, 0xba800000, v53
	v_fmamk_f32 v55, v69, 0xba800000, v55
	v_fmac_f32_e32 v52, 0xba800000, v69
	s_waitcnt lgkmcnt(0)
	v_add_f32_e32 v72, v72, v79
	ds_bpermute_b32 v79, v77, v72
	v_fmamk_f32 v50, v69, 0xba800000, v50
	v_fmamk_f32 v49, v69, 0xba800000, v49
	v_fmamk_f32 v51, v69, 0xba800000, v51
	v_fmac_f32_e32 v48, 0xba800000, v69
	s_waitcnt lgkmcnt(0)
	v_add_f32_e32 v72, v72, v79
	ds_bpermute_b32 v79, v78, v72
	s_waitcnt lgkmcnt(0)
	v_add_f32_e32 v79, v72, v79
	v_mul_f32_e32 v72, v61, v61
	v_fmamk_f32 v43, v79, 0xba800000, v43
	v_fmamk_f32 v41, v79, 0xba800000, v41
	v_fmac_f32_e32 v72, v60, v60
	v_fmamk_f32 v42, v79, 0xba800000, v42
	v_fmac_f32_e32 v40, 0xba800000, v79
	v_add_f32_e32 v72, v72, v80
	v_mul_f32_e32 v80, v41, v41
	v_mul_f32_e32 v81, v43, v43
	v_fmac_f32_e32 v80, v40, v40
	v_fmac_f32_e32 v81, v42, v42
	v_add_f32_e32 v80, v80, v81
	v_mul_f32_e32 v81, v57, v57
	v_fmac_f32_e32 v81, v56, v56
	v_fmamk_f32 v39, v79, 0xba800000, v39
	v_fmamk_f32 v37, v79, 0xba800000, v37
	v_add_f32_e32 v81, v81, v82
	v_fmamk_f32 v38, v79, 0xba800000, v38
	v_fmac_f32_e32 v36, 0xba800000, v79
	v_add_f32_e32 v72, v72, v81
	v_mul_f32_e32 v81, v37, v37
	v_mul_f32_e32 v82, v39, v39
	v_fmac_f32_e32 v81, v36, v36
	v_fmac_f32_e32 v82, v38, v38
	v_add_f32_e32 v81, v81, v82
	v_add_f32_e32 v80, v80, v81
	v_mul_f32_e32 v81, v53, v53
	v_mul_f32_e32 v82, v54, v54
	v_fmac_f32_e32 v81, v52, v52
	v_fmac_f32_e32 v82, v55, v55
	v_fmamk_f32 v35, v79, 0xba800000, v35
	v_fmamk_f32 v33, v79, 0xba800000, v33
	v_add_f32_e32 v81, v81, v82
	v_fmamk_f32 v34, v79, 0xba800000, v34
	v_fmac_f32_e32 v32, 0xba800000, v79
	v_add_f32_e32 v72, v81, v72
	v_mul_f32_e32 v81, v33, v33
	v_mul_f32_e32 v82, v35, v35
	v_fmac_f32_e32 v81, v32, v32
	v_fmac_f32_e32 v82, v34, v34
	v_add_f32_e32 v81, v81, v82
	v_add_f32_e32 v80, v81, v80
	v_mul_f32_e32 v81, v49, v49
	v_mul_f32_e32 v82, v50, v50
	v_fmac_f32_e32 v81, v48, v48
	v_fmac_f32_e32 v82, v51, v51
	v_fmamk_f32 v47, v79, 0xba800000, v47
	v_fmamk_f32 v45, v79, 0xba800000, v45
	v_add_f32_e32 v81, v81, v82
	v_fmamk_f32 v46, v79, 0xba800000, v46
	v_fmac_f32_e32 v44, 0xba800000, v79
	v_add_f32_e32 v72, v81, v72
	v_mul_f32_e32 v81, v45, v45
	v_mul_f32_e32 v82, v47, v47
	v_fmac_f32_e32 v81, v44, v44
	v_fmac_f32_e32 v82, v46, v46
	v_add_f32_e32 v81, v81, v82
	v_add_f32_e32 v80, v81, v80
	ds_bpermute_b32 v81, v73, v72
	s_waitcnt lgkmcnt(0)
	v_add_f32_e32 v72, v72, v81
	ds_bpermute_b32 v81, v74, v72
	s_waitcnt lgkmcnt(0)
	v_add_f32_e32 v72, v72, v81
	ds_bpermute_b32 v81, v75, v72
	s_waitcnt lgkmcnt(0)
	v_add_f32_e32 v72, v72, v81
	ds_bpermute_b32 v81, v76, v72
	s_waitcnt lgkmcnt(0)
	v_add_f32_e32 v72, v72, v81
	ds_bpermute_b32 v81, v77, v72
	s_waitcnt lgkmcnt(0)
	v_add_f32_e32 v72, v72, v81
	ds_bpermute_b32 v81, v78, v72
	s_waitcnt lgkmcnt(0)
	v_add_f32_e32 v72, v72, v81
	ds_bpermute_b32 v81, v73, v80
	v_fmamk_f32 v72, v72, 0x3a800000, v252
	v_rsq_f32_e32 v72, v72
	s_waitcnt lgkmcnt(0)
	v_add_f32_e32 v80, v80, v81
	ds_bpermute_b32 v81, v74, v80
	s_waitcnt lgkmcnt(0)
	v_add_f32_e32 v80, v80, v81
	ds_bpermute_b32 v81, v75, v80
	s_waitcnt lgkmcnt(0)
	v_add_f32_e32 v80, v80, v81
	ds_bpermute_b32 v81, v76, v80
	s_waitcnt lgkmcnt(0)
	v_add_f32_e32 v80, v80, v81
	ds_bpermute_b32 v81, v77, v80
	s_waitcnt lgkmcnt(0)
	v_add_f32_e32 v80, v80, v81
	ds_bpermute_b32 v81, v78, v80
	s_and_saveexec_b64 s[20:21], vcc
	s_cbranch_execz .LBB0_1829
;     ...
;         if (!dry) {
;             u32x2* xb = (u32x2*)(Xb + (size_t)row * DM);
;             if (l == 0) STATS[row] = (f32x2){mean, rstd};
	v_readlane_b32 s34, v254, 46
	v_readlane_b32 s35, v254, 47
	v_mul_f32_e32 v82, 0x3a800000, v69
	v_mov_b32_e32 v83, v72
	v_lshl_add_u64 v[84:85], v[70:71], 3, s[34:35]
	global_store_dwordx2 v[84:85], v[82:83], off
